# hand-written ffnconv v3 in both layers
# baseline (speedup 1.0000x reference)
.LBB0_2486:
.LBB0_2487:
	s_waitcnt vmcnt(0) lgkmcnt(0)
	s_load_dwordx4 s[0:3], s[92:93], 0xd8
	s_add_u32 s38, s90, 0x15918000
	s_addc_u32 s39, s91, 0
	s_add_u32 s40, s90, 0x21918000
	s_addc_u32 s41, s91, 0
	s_add_u32 s4, s90, 0x2c918180
	s_addc_u32 s5, s91, 0
	v_mov_b32_e32 v4, 0xbfb8aa3b
	v_mov_b32_e32 v5, 0xbfb8aa3b
	v_mov_b32_e32 v6, 1.0
	v_mov_b32_e32 v7, 1.0
	v_mov_b32_e32 v9, 0
	v_mov_b32_e32 v208, 1
	s_waitcnt lgkmcnt(0)
	s_add_u32 s0, s0, 0x63000
	s_addc_u32 s1, s1, 0
	s_add_u32 s2, s2, 0xb000
	s_addc_u32 s3, s3, 0
	v_readfirstlane_b32 s6, v154
	s_lshr_b32 s6, s6, 6
	s_lshl_b32 s6, s6, 8
	s_add_u32 s6, s6, s96

.Lffn_p19_done:
	s_waitcnt vmcnt(0)
	s_branch .LBB0_2563
.LBB0_2563:
	s_cmp_gt_i32 s87, 20
	s_cbranch_scc1 .LBB0_2661
	s_load_dword s0, s[92:93], 0x104
	s_waitcnt lgkmcnt(0)
	s_cmp_lt_i32 s0, 21
	s_cbranch_scc1 .LBB0_2661
	s_cmp_eq_u32 s87, 20
	s_cbranch_scc1 .LBB0_2633
	s_cmp_lt_u32 s0, 23
	s_mov_b64 s[0:1], -1
	s_cbranch_scc0 .LBB0_2620
	s_getreg_b32 s2, hwreg(HW_REG_XCC_ID, 0, 4)
	s_waitcnt vmcnt(0)
	s_waitcnt vmcnt(0)
	s_barrier
	s_mov_b64 s[0:1], exec
	v_readlane_b32 s4, v232, 4
	v_readlane_b32 s5, v232, 5
	s_and_b64 s[4:5], s[0:1], s[4:5]
	s_mov_b64 exec, s[4:5]
	s_cbranch_execz .LBB0_2619
	s_add_i32 s3, 0, 0x20000
	v_mov_b32_e32 v1, s3
	s_waitcnt vmcnt(0) expcnt(0) lgkmcnt(0)
	ds_read_b32 v3, v1
	s_add_i32 s3, 0, 0x20004
	v_mov_b32_e32 v1, s3
	ds_read_b32 v1, v1
	s_and_b32 s33, s2, 15
	s_waitcnt lgkmcnt(1)
	v_cmp_ne_u32_e32 vcc, 0, v3
	s_cbranch_vccnz .LBB0_2583
	s_add_u32 s2, s90, 0x2c918200
	s_addc_u32 s3, s91, 0
	s_add_u32 s4, s90, 0x2c918400
	s_addc_u32 s5, s91, 0
	s_add_u32 s6, s90, 0x2c918500
	s_addc_u32 s7, s91, 0
	s_add_u32 s8, s90, 0x2c918600
	s_addc_u32 s9, s91, 0
	s_add_u32 s10, s90, 0x2c918700
	s_addc_u32 s11, s91, 0
	s_add_u32 s12, s90, 0x2c918800
	s_addc_u32 s13, s91, 0
	s_add_u32 s14, s90, 0x2c918900
	s_addc_u32 s15, s91, 0
	s_add_u32 s16, s90, 0x2c918a00
	s_addc_u32 s17, s91, 0
	s_add_u32 s18, s90, 0x2c918b00
	s_addc_u32 s19, s91, 0
	s_add_u32 s20, s90, 0x2c918c00
	s_addc_u32 s21, s91, 0
	s_add_u32 s22, s90, 0x2c918d00
	s_addc_u32 s23, s91, 0
	s_add_u32 s24, s90, 0x2c918e00
	s_addc_u32 s25, s91, 0
	s_add_u32 s26, s90, 0x2c918f00
	s_addc_u32 s27, s91, 0
	s_add_u32 s28, s90, 0x2c919000
	s_addc_u32 s29, s91, 0
	s_add_u32 s30, s90, 0x2c919100
	s_addc_u32 s31, s91, 0
	s_add_u32 s34, s90, 0x2c919200
	s_addc_u32 s35, s91, 0
	s_mul_i32 s44, s95, s97
	s_add_u32 s36, s90, 0x2c919300
	s_mul_i32 s44, s44, s94
	s_addc_u32 s37, s91, 0
	s_mov_b32 s45, 1
	v_mov_b32_e32 v17, 0
	s_branch .LBB0_2571
